# transpose_jobs: row-gain multiply deferred from load time to emit time (gains kept in dedicated VGPRs) so scaled weight tiles overlap HBM latency
# baseline (speedup 1.0000x reference)
; DI void tr_load(const TDesc& d, int tid, f32x4 (&v)[8]) {
;   const int lane = tid & 63, w = tid >> 6, n = d.n0 + lane * 4;
;   const float* s = d.src; int col;
;   if (d.map == 0) col = n < d.Nsrc ? n : -1;
;   else if (d.map == 1) col = n < 3072 ? n : (n < 7168 ? n + 8 : (n < 7176 ? n - 7168 + 3072 : -1));
;   else { col = (n >> 5) * 16 + (n & 15); if (n & 16) s = d.src2; }
; #pragma unroll
;   for (int r = 0; r < 8; ++r) {
;     const int k = d.k0 + w * 8 + r;
;     v[r] = col >= 0 ? *(const f32x4*)(s + (size_t)k * d.Nsrc + col) : (f32x4){0.f, 0.f, 0.f, 0.f};
;   }
;   if (d.rscale) {
; #pragma unroll
;     for (int r = 0; r < 8; ++r) { const float g = d.rscale[d.k0 + w * 8 + r]; v[r] = v[r] * g; }
;   }
.LBB0_2175:
	s_or_b64 exec, exec, s[4:5]
	v_mov_b32_e32 v102, 1.0
	v_mov_b32_e32 v104, 1.0
	v_mov_b32_e32 v106, 1.0
	v_mov_b32_e32 v108, 1.0
	v_mov_b32_e32 v110, 1.0
	v_mov_b32_e32 v112, 1.0
	v_mov_b32_e32 v114, 1.0
	v_mov_b32_e32 v116, 1.0
	s_cmp_lg_u64 s[30:31], 0
	s_cbranch_scc0 .LBB0_2177
	v_ashrrev_i32_e32 v3, 31, v2
	v_lshl_add_u64 v[36:37], v[2:3], 2, s[30:31]
	v_add_u32_e32 v40, 1, v2
	v_add_u32_e32 v42, 2, v2
	v_add_u32_e32 v44, 3, v2
	v_add_u32_e32 v46, 4, v2
	v_add_u32_e32 v48, 5, v2
	v_add_u32_e32 v2, 6, v2
	v_ashrrev_i32_e32 v41, 31, v40
	v_ashrrev_i32_e32 v43, 31, v42
	v_ashrrev_i32_e32 v45, 31, v44
	v_ashrrev_i32_e32 v47, 31, v46
	v_ashrrev_i32_e32 v39, 31, v38
	v_ashrrev_i32_e32 v49, 31, v48
	v_ashrrev_i32_e32 v3, 31, v2
	v_lshl_add_u64 v[40:41], v[40:41], 2, s[30:31]
	v_lshl_add_u64 v[42:43], v[42:43], 2, s[30:31]
	v_lshl_add_u64 v[44:45], v[44:45], 2, s[30:31]
	v_lshl_add_u64 v[46:47], v[46:47], 2, s[30:31]
	v_lshl_add_u64 v[38:39], v[38:39], 2, s[30:31]
	v_lshl_add_u64 v[48:49], v[48:49], 2, s[30:31]
	v_lshl_add_u64 v[2:3], v[2:3], 2, s[30:31]
	global_load_dword v102, v[36:37], off
	s_nop 0
	global_load_dword v104, v[40:41], off
	s_nop 0
	global_load_dword v116, v[38:39], off
	s_nop 0
	global_load_dword v106, v[42:43], off
	s_nop 0
	global_load_dword v108, v[44:45], off
	s_nop 0
	global_load_dword v110, v[46:47], off
	global_load_dword v112, v[48:49], off
	global_load_dword v114, v[2:3], off

; DI void tr_load(const TDesc& d, int tid, f32x4 (&v)[8]) {
;   const int lane = tid & 63, w = tid >> 6, n = d.n0 + lane * 4;
;   const float* s = d.src; int col;
;   if (d.map == 0) col = n < d.Nsrc ? n : -1;
;   else if (d.map == 1) col = n < 3072 ? n : (n < 7168 ? n + 8 : (n < 7176 ? n - 7168 + 3072 : -1));
;   else { col = (n >> 5) * 16 + (n & 15); if (n & 16) s = d.src2; }
; #pragma unroll
;   for (int r = 0; r < 8; ++r) {
;     const int k = d.k0 + w * 8 + r;
;     v[r] = col >= 0 ? *(const f32x4*)(s + (size_t)k * d.Nsrc + col) : (f32x4){0.f, 0.f, 0.f, 0.f};
;   }
;   if (d.rscale) {
; #pragma unroll
;     for (int r = 0; r < 8; ++r) { const float g = d.rscale[d.k0 + w * 8 + r]; v[r] = v[r] * g; }
;   }
.LBB0_2293:
	s_or_b64 exec, exec, s[4:5]
	v_mov_b32_e32 v118, 1.0
	v_mov_b32_e32 v120, 1.0
	v_mov_b32_e32 v122, 1.0
	v_mov_b32_e32 v124, 1.0
	v_mov_b32_e32 v126, 1.0
	v_mov_b32_e32 v128, 1.0
	v_mov_b32_e32 v130, 1.0
	v_mov_b32_e32 v132, 1.0
	s_cmp_lg_u64 s[26:27], 0
	s_cbranch_scc0 .LBB0_2295
	v_ashrrev_i32_e32 v3, 31, v2
	v_lshl_add_u64 v[68:69], v[2:3], 2, s[26:27]
	v_add_u32_e32 v74, 1, v2
	v_add_u32_e32 v76, 2, v2
	v_add_u32_e32 v78, 3, v2
	v_add_u32_e32 v80, 4, v2
	v_add_u32_e32 v82, 5, v2
	v_add_u32_e32 v2, 6, v2
	v_ashrrev_i32_e32 v75, 31, v74
	v_ashrrev_i32_e32 v77, 31, v76
	v_ashrrev_i32_e32 v79, 31, v78
	v_ashrrev_i32_e32 v81, 31, v80
	v_ashrrev_i32_e32 v71, 31, v70
	v_ashrrev_i32_e32 v83, 31, v82
	v_ashrrev_i32_e32 v3, 31, v2
	v_lshl_add_u64 v[74:75], v[74:75], 2, s[26:27]
	v_lshl_add_u64 v[76:77], v[76:77], 2, s[26:27]
	v_lshl_add_u64 v[78:79], v[78:79], 2, s[26:27]
	v_lshl_add_u64 v[80:81], v[80:81], 2, s[26:27]
	v_lshl_add_u64 v[70:71], v[70:71], 2, s[26:27]
	v_lshl_add_u64 v[82:83], v[82:83], 2, s[26:27]
	v_lshl_add_u64 v[2:3], v[2:3], 2, s[26:27]
	global_load_dword v118, v[68:69], off
	s_nop 0
	global_load_dword v120, v[74:75], off
	s_nop 0
	global_load_dword v132, v[70:71], off
	s_nop 0
	global_load_dword v122, v[76:77], off
	s_nop 0
	global_load_dword v124, v[78:79], off
	s_nop 0
	global_load_dword v126, v[80:81], off
	global_load_dword v128, v[82:83], off
	global_load_dword v130, v[2:3], off

; DI bool decode_tile(const Params& p, int gi, TDesc& d) {
.LBB0_2299:
	s_andn2_b64 vcc, exec, s[2:3]
	s_mov_b64 s[36:37], -1
	s_cbranch_vccnz .LBB0_2298
	v_readlane_b32 s2, v250, 1
	s_add_i32 s65, s65, s2
	v_readlane_b32 s3, v250, 2
	s_cmpk_gt_i32 s65, 0x15ff
	s_cselect_b64 s[2:3], -1, 0
	s_mov_b64 s[34:35], -1
	s_and_b64 vcc, exec, s[2:3]
	s_waitcnt vmcnt(0)
	v_pk_mul_f32 v[4:5], v[4:5], v[102:103] op_sel_hi:[1,0]
	v_pk_mul_f32 v[6:7], v[6:7], v[102:103] op_sel_hi:[1,0]
	v_pk_mul_f32 v[8:9], v[8:9], v[104:105] op_sel_hi:[1,0]
	v_pk_mul_f32 v[10:11], v[10:11], v[104:105] op_sel_hi:[1,0]
	v_pk_mul_f32 v[12:13], v[12:13], v[106:107] op_sel_hi:[1,0]
	v_pk_mul_f32 v[14:15], v[14:15], v[106:107] op_sel_hi:[1,0]
	v_pk_mul_f32 v[16:17], v[16:17], v[108:109] op_sel_hi:[1,0]
	v_pk_mul_f32 v[18:19], v[18:19], v[108:109] op_sel_hi:[1,0]
	v_pk_mul_f32 v[20:21], v[20:21], v[110:111] op_sel_hi:[1,0]
	v_pk_mul_f32 v[22:23], v[22:23], v[110:111] op_sel_hi:[1,0]
	v_pk_mul_f32 v[24:25], v[24:25], v[112:113] op_sel_hi:[1,0]
	v_pk_mul_f32 v[26:27], v[26:27], v[112:113] op_sel_hi:[1,0]
	v_pk_mul_f32 v[28:29], v[28:29], v[114:115] op_sel_hi:[1,0]
	v_pk_mul_f32 v[30:31], v[30:31], v[114:115] op_sel_hi:[1,0]
	v_pk_mul_f32 v[32:33], v[32:33], v[116:117] op_sel_hi:[1,0]
	v_pk_mul_f32 v[34:35], v[34:35], v[116:117] op_sel_hi:[1,0]
	ds_write_b128 v98, v[4:7]
	ds_write_b128 v98, v[8:11] offset:1040
	ds_write_b128 v98, v[12:15] offset:2080
	ds_write_b128 v98, v[16:19] offset:3120
	ds_write_b128 v98, v[20:23] offset:4160
	ds_write_b128 v98, v[24:27] offset:5200
	ds_write_b128 v98, v[28:31] offset:6240
	ds_write_b128 v99, v[32:35]
	s_waitcnt lgkmcnt(0)
	s_barrier
	s_cbranch_vccnz .LBB0_2302
	s_mul_hi_i32 s4, s65, 0x2e8ba2e9
	s_lshr_b32 s5, s4, 31
	s_ashr_i32 s4, s4, 8
	s_add_i32 s6, s4, s5
	s_mul_i32 s4, s6, 0x580
	v_readlane_b32 s80, v250, 41
	s_sub_i32 s33, s65, s4
	s_ashr_i32 s7, s6, 31
	s_mul_i32 s10, s6, 0x2c00000
	v_readlane_b32 s88, v250, 49
	s_mul_hi_i32 s11, s6, 0x2c00000
	v_readlane_b32 s89, v250, 50
	s_add_u32 s8, s88, s10
	v_readlane_b32 s90, v250, 51
	s_addc_u32 s9, s89, s11
	v_readlane_b32 s91, v250, 52
	s_add_u32 s34, s90, s10
	v_readlane_b32 s4, v250, 57
	v_readlane_b32 s81, v250, 42
	v_readlane_b32 s82, v250, 43
	v_readlane_b32 s83, v250, 44
	v_readlane_b32 s84, v250, 45
	v_readlane_b32 s85, v250, 46
	v_readlane_b32 s86, v250, 47
	v_readlane_b32 s87, v250, 48
	v_readlane_b32 s92, v250, 53
	v_readlane_b32 s93, v250, 54
	v_readlane_b32 s94, v250, 55
	v_readlane_b32 s95, v250, 56
	s_addc_u32 s35, s91, s11
	v_readlane_b32 s5, v250, 58
	s_and_b64 s[4:5], s[4:5], exec
	v_readlane_b32 s80, v252, 47
	s_cselect_b32 s5, 0, s35
	s_cselect_b32 s4, 0, s34
	s_lshl_b64 s[6:7], s[6:7], 13
	v_readlane_b32 s88, v252, 55
	v_readlane_b32 s89, v252, 56
	s_add_u32 s34, s88, s6
	s_addc_u32 s35, s89, s7
	v_readlane_b32 s6, v250, 63
	v_readlane_b32 s7, v251, 0
	s_and_b64 s[6:7], s[6:7], exec
	s_cselect_b32 s7, 0, s35
	s_cselect_b32 s6, 0, s34
	s_add_u32 s10, s41, s10
	s_mul_i32 s34, s33, 0xba3
	s_addc_u32 s11, s42, s11
	s_lshr_b32 s35, s34, 31
	s_ashr_i32 s34, s34, 17
	s_add_i32 s34, s34, s35
	s_lshl_b32 s69, s34, 6
	s_mul_i32 s34, s34, 44
	s_sub_i32 s33, s33, s34
	v_readlane_b32 s81, v252, 48
	v_readlane_b32 s85, v252, 52
	s_sext_i32_i16 s33, s33
	s_mov_b32 s85, 0xbfb8aa3b
	s_movk_i32 s81, 0x2000
	s_lshl_b32 s68, s33, 8
	s_mov_b64 s[34:35], 0
	v_readlane_b32 s82, v252, 49
	v_readlane_b32 s83, v252, 50
	v_readlane_b32 s84, v252, 51
	v_readlane_b32 s86, v252, 53
	v_readlane_b32 s87, v252, 54
	v_readlane_b32 s90, v252, 57
	v_readlane_b32 s91, v252, 58
	v_readlane_b32 s92, v252, 59
	v_readlane_b32 s93, v252, 60
	v_readlane_b32 s94, v252, 61
	v_readlane_b32 s95, v252, 62

; DI void tr_load(const TDesc& d, int tid, f32x4 (&v)[8]) {
;   const int lane = tid & 63, w = tid >> 6, n = d.n0 + lane * 4;
;   const float* s = d.src; int col;
;   if (d.map == 0) col = n < d.Nsrc ? n : -1;
;   else if (d.map == 1) col = n < 3072 ? n : (n < 7168 ? n + 8 : (n < 7176 ? n - 7168 + 3072 : -1));
;   else { col = (n >> 5) * 16 + (n & 15); if (n & 16) s = d.src2; }
; #pragma unroll
;   for (int r = 0; r < 8; ++r) {
;     const int k = d.k0 + w * 8 + r;
;     v[r] = col >= 0 ? *(const f32x4*)(s + (size_t)k * d.Nsrc + col) : (f32x4){0.f, 0.f, 0.f, 0.f};
;   }
;   if (d.rscale) {
; #pragma unroll
;     for (int r = 0; r < 8; ++r) { const float g = d.rscale[d.k0 + w * 8 + r]; v[r] = v[r] * g; }
;   }
.LBB0_2408:
	s_or_b64 exec, exec, s[20:21]
	v_mov_b32_e32 v102, 1.0
	v_mov_b32_e32 v104, 1.0
	v_mov_b32_e32 v106, 1.0
	v_mov_b32_e32 v108, 1.0
	v_mov_b32_e32 v110, 1.0
	v_mov_b32_e32 v112, 1.0
	v_mov_b32_e32 v114, 1.0
	v_mov_b32_e32 v116, 1.0
	s_cmp_lg_u64 s[6:7], 0
	s_cbranch_scc0 .LBB0_2410
	v_ashrrev_i32_e32 v71, 31, v70
	v_lshl_add_u64 v[2:3], v[70:71], 2, s[6:7]
	v_ashrrev_i32_e32 v73, 31, v72
	v_ashrrev_i32_e32 v77, 31, v76
	v_ashrrev_i32_e32 v79, 31, v78
	v_ashrrev_i32_e32 v83, 31, v82
	v_ashrrev_i32_e32 v81, 31, v80
	v_ashrrev_i32_e32 v85, 31, v84
	v_ashrrev_i32_e32 v87, 31, v86
	global_load_dword v102, v[2:3], off
	v_lshl_add_u64 v[2:3], v[72:73], 2, s[6:7]
	v_lshl_add_u64 v[70:71], v[76:77], 2, s[6:7]
	v_lshl_add_u64 v[72:73], v[78:79], 2, s[6:7]
	v_lshl_add_u64 v[74:75], v[82:83], 2, s[6:7]
	v_lshl_add_u64 v[76:77], v[80:81], 2, s[6:7]
	v_lshl_add_u64 v[78:79], v[84:85], 2, s[6:7]
	v_lshl_add_u64 v[80:81], v[86:87], 2, s[6:7]
	global_load_dword v104, v[2:3], off
	s_nop 0
	global_load_dword v106, v[70:71], off
	s_nop 0
	global_load_dword v108, v[72:73], off
	s_nop 0
	global_load_dword v110, v[74:75], off
	s_nop 0
	global_load_dword v112, v[76:77], off
	s_nop 0
	global_load_dword v114, v[78:79], off
	global_load_dword v116, v[80:81], off
.LBB0_2410:
	v_add_u32_e32 v0, s71, v97
	v_mad_i64_i32 v[2:3], s[20:21], v0, s17, 0
	ds_read_b32 v0, v100
	ds_read_b32 v70, v100 offset:1040
	ds_read_b32 v71, v100 offset:2080
	ds_read_b32 v72, v100 offset:3120
	ds_read_b32 v73, v100 offset:4160
	ds_read_b32 v74, v100 offset:5200
	ds_read_b32 v75, v100 offset:6240
	ds_read_b32 v76, v100 offset:7280
	s_waitcnt lgkmcnt(6)
	v_cvt_pk_bf16_f32 v70, v0, v70
	s_waitcnt lgkmcnt(4)
	v_cvt_pk_bf16_f32 v71, v71, v72
	s_waitcnt lgkmcnt(2)
	v_cvt_pk_bf16_f32 v72, v73, v74
	v_lshl_add_u64 v[2:3], v[2:3], 1, s[18:19]
	s_waitcnt lgkmcnt(0)
	v_cvt_pk_bf16_f32 v73, v75, v76
	ds_read_b32 v0, v100 offset:16640
	ds_read_b32 v74, v100 offset:17680
	ds_read_b32 v75, v100 offset:18720
	ds_read_b32 v76, v100 offset:19760
	ds_read_b32 v77, v100 offset:20800
	ds_read_b32 v78, v100 offset:21840
	ds_read_b32 v79, v100 offset:22880
	ds_read_b32 v80, v100 offset:23920
	s_ashr_i32 s17, s16, 31
	v_lshl_add_u64 v[2:3], s[16:17], 1, v[2:3]
	v_lshl_add_u64 v[2:3], v[68:69], 1, v[2:3]
	global_store_dwordx4 v[2:3], v[70:73], off
	s_andn2_b64 vcc, exec, s[22:23]
	s_mov_b64 s[34:35], 0
	s_waitcnt lgkmcnt(6)
	v_cvt_pk_bf16_f32 v70, v0, v74
	s_waitcnt lgkmcnt(4)
	v_cvt_pk_bf16_f32 v71, v75, v76
	s_waitcnt lgkmcnt(2)
	v_cvt_pk_bf16_f32 v72, v77, v78
	s_waitcnt lgkmcnt(0)
	v_cvt_pk_bf16_f32 v73, v79, v80
	ds_read_b32 v0, v100 offset:33280
	ds_read_b32 v74, v100 offset:34320
	ds_read_b32 v75, v100 offset:35360
	ds_read_b32 v76, v100 offset:36400
	ds_read_b32 v77, v100 offset:37440
	ds_read_b32 v78, v100 offset:38480
	ds_read_b32 v79, v100 offset:39520
	ds_read_b32 v80, v100 offset:40560
	global_store_dwordx4 v[2:3], v[70:73], off offset:32
	s_waitcnt lgkmcnt(6)
	s_nop 0
	v_cvt_pk_bf16_f32 v70, v0, v74
	s_waitcnt lgkmcnt(4)
	v_cvt_pk_bf16_f32 v71, v75, v76
	s_waitcnt lgkmcnt(2)
	v_cvt_pk_bf16_f32 v72, v77, v78
	s_waitcnt lgkmcnt(0)
	v_cvt_pk_bf16_f32 v73, v79, v80
	ds_read_b32 v0, v100 offset:49920
	ds_read_b32 v74, v100 offset:50960
	ds_read_b32 v75, v100 offset:52000
	ds_read_b32 v76, v100 offset:53040
	ds_read_b32 v77, v100 offset:54080
	ds_read_b32 v78, v100 offset:55120
	ds_read_b32 v79, v100 offset:56160
	ds_read_b32 v80, v100 offset:57200
	global_store_dwordx4 v[2:3], v[70:73], off offset:64
	s_waitcnt lgkmcnt(6)
	s_nop 0
	v_cvt_pk_bf16_f32 v70, v0, v74
	s_waitcnt lgkmcnt(4)
	v_cvt_pk_bf16_f32 v71, v75, v76
	s_waitcnt lgkmcnt(2)
	v_cvt_pk_bf16_f32 v72, v77, v78
	s_waitcnt lgkmcnt(0)
	v_cvt_pk_bf16_f32 v73, v79, v80
	global_store_dwordx4 v[2:3], v[70:73], off offset:96
	s_barrier
	s_cbranch_vccnz .LBB0_2296
	v_readlane_b32 s16, v250, 1
	s_add_i32 s65, s65, s16
	s_cmpk_gt_i32 s65, 0x15ff
	s_cselect_b64 s[34:35], -1, 0
	v_readlane_b32 s17, v250, 2
	s_mov_b64 s[36:37], -1
	s_and_b64 vcc, exec, s[34:35]
	v_pk_mul_f32 v[40:41], v[40:41], v[118:119] op_sel_hi:[1,0]
	v_pk_mul_f32 v[42:43], v[42:43], v[118:119] op_sel_hi:[1,0]
	v_pk_mul_f32 v[36:37], v[36:37], v[120:121] op_sel_hi:[1,0]
	v_pk_mul_f32 v[38:39], v[38:39], v[120:121] op_sel_hi:[1,0]
	v_pk_mul_f32 v[48:49], v[48:49], v[122:123] op_sel_hi:[1,0]
	v_pk_mul_f32 v[50:51], v[50:51], v[122:123] op_sel_hi:[1,0]
	v_pk_mul_f32 v[44:45], v[44:45], v[124:125] op_sel_hi:[1,0]
	v_pk_mul_f32 v[46:47], v[46:47], v[124:125] op_sel_hi:[1,0]
	v_pk_mul_f32 v[56:57], v[56:57], v[126:127] op_sel_hi:[1,0]
	v_pk_mul_f32 v[58:59], v[58:59], v[126:127] op_sel_hi:[1,0]
	v_pk_mul_f32 v[52:53], v[52:53], v[128:129] op_sel_hi:[1,0]
	v_pk_mul_f32 v[54:55], v[54:55], v[128:129] op_sel_hi:[1,0]
	v_pk_mul_f32 v[64:65], v[64:65], v[130:131] op_sel_hi:[1,0]
	v_pk_mul_f32 v[66:67], v[66:67], v[130:131] op_sel_hi:[1,0]
	v_pk_mul_f32 v[60:61], v[60:61], v[132:133] op_sel_hi:[1,0]
	v_pk_mul_f32 v[62:63], v[62:63], v[132:133] op_sel_hi:[1,0]
	ds_write_b128 v98, v[40:43]
	ds_write_b128 v98, v[36:39] offset:1040
	ds_write_b128 v98, v[48:51] offset:2080
	ds_write_b128 v98, v[44:47] offset:3120
	ds_write_b128 v98, v[56:59] offset:4160
	ds_write_b128 v98, v[52:55] offset:5200
	ds_write_b128 v98, v[64:67] offset:6240
	ds_write_b128 v99, v[60:63]
	s_waitcnt lgkmcnt(0)
	s_barrier
	s_cbranch_vccnz .LBB0_2413
	s_mul_hi_i32 s16, s65, 0x2e8ba2e9
	s_lshr_b32 s17, s16, 31
	s_ashr_i32 s16, s16, 8
	s_add_i32 s16, s16, s17
	s_mul_i32 s17, s16, 0x580
	v_readlane_b32 s80, v250, 41
	s_sub_i32 s33, s65, s17
	s_ashr_i32 s17, s16, 31
	s_mul_i32 s37, s16, 0x2c00000
	v_readlane_b32 s88, v250, 49
	s_mul_hi_i32 s36, s16, 0x2c00000
	v_readlane_b32 s89, v250, 50
	s_add_u32 s22, s88, s37
	v_readlane_b32 s90, v250, 51
	s_addc_u32 s23, s89, s36
	v_readlane_b32 s91, v250, 52
	s_add_u32 s20, s90, s37
	v_readlane_b32 s18, v250, 57
	v_readlane_b32 s81, v250, 42
	v_readlane_b32 s82, v250, 43
	v_readlane_b32 s83, v250, 44
	v_readlane_b32 s84, v250, 45
	v_readlane_b32 s85, v250, 46
	v_readlane_b32 s86, v250, 47
	v_readlane_b32 s87, v250, 48
	v_readlane_b32 s92, v250, 53
	v_readlane_b32 s93, v250, 54
	v_readlane_b32 s94, v250, 55
	v_readlane_b32 s95, v250, 56
	s_addc_u32 s21, s91, s36
	v_readlane_b32 s19, v250, 58
	s_and_b64 s[18:19], s[18:19], exec
	v_readlane_b32 s80, v252, 47
	s_cselect_b32 s21, 0, s21
	s_cselect_b32 s20, 0, s20
	s_lshl_b64 s[16:17], s[16:17], 13
	v_readlane_b32 s88, v252, 55
	v_readlane_b32 s89, v252, 56
	s_add_u32 s18, s88, s16
	s_addc_u32 s19, s89, s17
	v_readlane_b32 s16, v250, 63
	v_readlane_b32 s17, v251, 0
	s_and_b64 s[16:17], s[16:17], exec
	s_cselect_b32 s31, 0, s19
	s_cselect_b32 s30, 0, s18
	s_add_u32 s16, s41, s37
	s_mul_i32 s18, s33, 0xba3
	s_addc_u32 s17, s42, s36
	s_lshr_b32 s19, s18, 31
	s_ashr_i32 s18, s18, 17
	s_add_i32 s19, s18, s19
	s_lshl_b32 s18, s19, 6
	s_mul_i32 s19, s19, 44
	s_sub_i32 s19, s33, s19
	v_readlane_b32 s81, v252, 48
	v_readlane_b32 s85, v252, 52
	s_sext_i32_i16 s19, s19
	s_mov_b32 s85, 0xbfb8aa3b
	s_movk_i32 s81, 0x2000
	s_lshl_b32 s19, s19, 8
	s_mov_b64 s[36:37], 0
	v_readlane_b32 s82, v252, 49
	v_readlane_b32 s83, v252, 50
	v_readlane_b32 s84, v252, 51
	v_readlane_b32 s86, v252, 53
	v_readlane_b32 s87, v252, 54
	v_readlane_b32 s90, v252, 57
	v_readlane_b32 s91, v252, 58
	v_readlane_b32 s92, v252, 59
	v_readlane_b32 s93, v252, 60
	v_readlane_b32 s94, v252, 61
	v_readlane_b32 s95, v252, 62

; DI void tr_load(const TDesc& d, int tid, f32x4 (&v)[8]) {
;   const int lane = tid & 63, w = tid >> 6, n = d.n0 + lane * 4;
;   const float* s = d.src; int col;
;   if (d.map == 0) col = n < d.Nsrc ? n : -1;
;   else if (d.map == 1) col = n < 3072 ? n : (n < 7168 ? n + 8 : (n < 7176 ? n - 7168 + 3072 : -1));
;   else { col = (n >> 5) * 16 + (n & 15); if (n & 16) s = d.src2; }
; #pragma unroll
;   for (int r = 0; r < 8; ++r) {
;     const int k = d.k0 + w * 8 + r;
;     v[r] = col >= 0 ? *(const f32x4*)(s + (size_t)k * d.Nsrc + col) : (f32x4){0.f, 0.f, 0.f, 0.f};
;   }
;   if (d.rscale) {
; #pragma unroll
;     for (int r = 0; r < 8; ++r) { const float g = d.rscale[d.k0 + w * 8 + r]; v[r] = v[r] * g; }
;   }
.LBB0_2520:
	s_or_b64 exec, exec, s[24:25]
	v_mov_b32_e32 v118, 1.0
	v_mov_b32_e32 v120, 1.0
	v_mov_b32_e32 v122, 1.0
	v_mov_b32_e32 v124, 1.0
	v_mov_b32_e32 v126, 1.0
	v_mov_b32_e32 v128, 1.0
	v_mov_b32_e32 v130, 1.0
	v_mov_b32_e32 v132, 1.0
	s_cmp_lg_u64 s[30:31], 0
	s_cbranch_scc0 .LBB0_2522
	v_ashrrev_i32_e32 v3, 31, v2
	v_lshl_add_u64 v[2:3], v[2:3], 2, s[30:31]
	v_ashrrev_i32_e32 v71, 31, v70
	v_ashrrev_i32_e32 v75, 31, v74
	v_ashrrev_i32_e32 v77, 31, v76
	v_ashrrev_i32_e32 v79, 31, v78
	v_ashrrev_i32_e32 v81, 31, v80
	v_ashrrev_i32_e32 v83, 31, v82
	v_ashrrev_i32_e32 v85, 31, v84
	global_load_dword v118, v[2:3], off
	v_lshl_add_u64 v[2:3], v[70:71], 2, s[30:31]
	v_lshl_add_u64 v[70:71], v[74:75], 2, s[30:31]
	v_lshl_add_u64 v[72:73], v[76:77], 2, s[30:31]
	v_lshl_add_u64 v[74:75], v[78:79], 2, s[30:31]
	v_lshl_add_u64 v[76:77], v[80:81], 2, s[30:31]
	v_lshl_add_u64 v[78:79], v[82:83], 2, s[30:31]
	v_lshl_add_u64 v[80:81], v[84:85], 2, s[30:31]
	global_load_dword v120, v[2:3], off
	s_nop 0
	global_load_dword v122, v[70:71], off
	s_nop 0
	global_load_dword v124, v[72:73], off
	s_nop 0
	global_load_dword v126, v[74:75], off
	s_nop 0
	global_load_dword v128, v[76:77], off
	s_nop 0
	global_load_dword v130, v[78:79], off
	global_load_dword v132, v[80:81], off

; DI bool decode_tile(const Params& p, int gi, TDesc& d) {
; DI void transpose_jobs(const Params& p) {
;     ...
;     if (!ha) { while (hb) { TR_EMIT(vb, db); hb = h_; } break; }
.LBB0_2524:
	v_readlane_b32 s0, v250, 1
	s_add_i32 s65, s65, s0
	s_cmpk_gt_i32 s65, 0x15ff
	s_cselect_b64 s[14:15], -1, 0
	v_readlane_b32 s1, v250, 2
	s_mov_b64 s[28:29], -1
	s_and_b64 vcc, exec, s[14:15]
	s_waitcnt vmcnt(4)
	v_pk_mul_f32 v[40:41], v[40:41], v[118:119] op_sel_hi:[1,0]
	v_pk_mul_f32 v[42:43], v[42:43], v[118:119] op_sel_hi:[1,0]
	v_pk_mul_f32 v[36:37], v[36:37], v[120:121] op_sel_hi:[1,0]
	v_pk_mul_f32 v[38:39], v[38:39], v[120:121] op_sel_hi:[1,0]
	v_pk_mul_f32 v[48:49], v[48:49], v[122:123] op_sel_hi:[1,0]
	v_pk_mul_f32 v[50:51], v[50:51], v[122:123] op_sel_hi:[1,0]
	v_pk_mul_f32 v[44:45], v[44:45], v[124:125] op_sel_hi:[1,0]
	v_pk_mul_f32 v[46:47], v[46:47], v[124:125] op_sel_hi:[1,0]
	v_pk_mul_f32 v[56:57], v[56:57], v[126:127] op_sel_hi:[1,0]
	v_pk_mul_f32 v[58:59], v[58:59], v[126:127] op_sel_hi:[1,0]
	v_pk_mul_f32 v[52:53], v[52:53], v[128:129] op_sel_hi:[1,0]
	v_pk_mul_f32 v[54:55], v[54:55], v[128:129] op_sel_hi:[1,0]
	v_pk_mul_f32 v[64:65], v[64:65], v[130:131] op_sel_hi:[1,0]
	v_pk_mul_f32 v[66:67], v[66:67], v[130:131] op_sel_hi:[1,0]
	v_pk_mul_f32 v[60:61], v[60:61], v[132:133] op_sel_hi:[1,0]
	v_pk_mul_f32 v[62:63], v[62:63], v[132:133] op_sel_hi:[1,0]
	ds_write_b128 v98, v[40:43]
	ds_write_b128 v98, v[36:39] offset:1040
	ds_write_b128 v98, v[48:51] offset:2080
	ds_write_b128 v98, v[44:47] offset:3120
	ds_write_b128 v98, v[56:59] offset:4160
	ds_write_b128 v98, v[52:55] offset:5200
	ds_write_b128 v98, v[64:67] offset:6240
	ds_write_b128 v99, v[60:63]
	s_waitcnt lgkmcnt(0)
	s_barrier
	s_cbranch_vccnz .LBB0_2526
	s_mul_hi_i32 s0, s65, 0x2e8ba2e9
	s_lshr_b32 s1, s0, 31
	s_ashr_i32 s0, s0, 8
	s_add_i32 s12, s0, s1
	s_mul_i32 s0, s12, 0xfffffa80
	v_readlane_b32 s80, v250, 41
	s_add_i32 s28, s65, s0
	s_ashr_i32 s13, s12, 31
	s_mul_i32 s33, s12, 0x2c00000
	v_readlane_b32 s88, v250, 49
	s_mul_hi_i32 s29, s12, 0x2c00000
	v_readlane_b32 s89, v250, 50
	s_add_u32 s26, s88, s33
	v_readlane_b32 s90, v250, 51
	s_addc_u32 s27, s89, s29
	v_readlane_b32 s91, v250, 52
	s_add_u32 s24, s90, s33
	v_readlane_b32 s0, v250, 57
	v_readlane_b32 s81, v250, 42
	v_readlane_b32 s82, v250, 43
	v_readlane_b32 s83, v250, 44
	v_readlane_b32 s84, v250, 45
	v_readlane_b32 s85, v250, 46
	v_readlane_b32 s86, v250, 47
	v_readlane_b32 s87, v250, 48
	v_readlane_b32 s92, v250, 53
	v_readlane_b32 s93, v250, 54
	v_readlane_b32 s94, v250, 55
	v_readlane_b32 s95, v250, 56
	s_addc_u32 s25, s91, s29
	v_readlane_b32 s1, v250, 58
	s_and_b64 s[0:1], s[0:1], exec
	v_readlane_b32 s80, v252, 47
	s_cselect_b32 s1, 0, s25
	s_cselect_b32 s0, 0, s24
	s_lshl_b64 s[12:13], s[12:13], 13
	v_readlane_b32 s88, v252, 55
	v_readlane_b32 s89, v252, 56
	s_add_u32 s24, s88, s12
	s_addc_u32 s25, s89, s13
	v_readlane_b32 s12, v250, 63
	v_readlane_b32 s13, v251, 0
	s_and_b64 s[12:13], s[12:13], exec
	s_cselect_b32 s25, 0, s25
	s_cselect_b32 s24, 0, s24
	s_add_u32 s12, s41, s33
	s_addc_u32 s13, s42, s29
	s_mul_i32 s29, s28, 0xba3
	s_lshr_b32 s33, s29, 31
	s_ashr_i32 s29, s29, 17
	s_add_i32 s29, s29, s33
	s_lshl_b32 s33, s29, 6
	s_mul_i32 s29, s29, 44
	s_sub_i32 s28, s28, s29
	v_readlane_b32 s81, v252, 48
	v_readlane_b32 s85, v252, 52
	s_sext_i32_i16 s28, s28
	s_mov_b32 s85, 0xbfb8aa3b
	s_movk_i32 s81, 0x2000
	s_lshl_b32 s36, s28, 8
	s_mov_b64 s[28:29], 0
	v_readlane_b32 s82, v252, 49
	v_readlane_b32 s83, v252, 50
	v_readlane_b32 s84, v252, 51
	v_readlane_b32 s86, v252, 53
	v_readlane_b32 s87, v252, 54
	v_readlane_b32 s90, v252, 57
	v_readlane_b32 s91, v252, 58
	v_readlane_b32 s92, v252, 59
	v_readlane_b32 s93, v252, 60
	v_readlane_b32 s94, v252, 61
	v_readlane_b32 s95, v252, 62

; DI void tr_load(const TDesc& d, int tid, f32x4 (&v)[8]) {
;   const int lane = tid & 63, w = tid >> 6, n = d.n0 + lane * 4;
;   const float* s = d.src; int col;
;   if (d.map == 0) col = n < d.Nsrc ? n : -1;
;   else if (d.map == 1) col = n < 3072 ? n : (n < 7168 ? n + 8 : (n < 7176 ? n - 7168 + 3072 : -1));
;   else { col = (n >> 5) * 16 + (n & 15); if (n & 16) s = d.src2; }
; #pragma unroll
;   for (int r = 0; r < 8; ++r) {
;     const int k = d.k0 + w * 8 + r;
;     v[r] = col >= 0 ? *(const f32x4*)(s + (size_t)k * d.Nsrc + col) : (f32x4){0.f, 0.f, 0.f, 0.f};
;   }
;   if (d.rscale) {
; #pragma unroll
;     for (int r = 0; r < 8; ++r) { const float g = d.rscale[d.k0 + w * 8 + r]; v[r] = v[r] * g; }
;   }
.LBB0_2630:
	s_or_b64 exec, exec, s[14:15]
	v_mov_b32_e32 v118, 1.0
	v_mov_b32_e32 v120, 1.0
	v_mov_b32_e32 v122, 1.0
	v_mov_b32_e32 v124, 1.0
	v_mov_b32_e32 v126, 1.0
	v_mov_b32_e32 v128, 1.0
	v_mov_b32_e32 v130, 1.0
	v_mov_b32_e32 v132, 1.0
	s_cmp_lg_u64 s[30:31], 0
	s_cbranch_scc0 .LBB0_2632
	v_ashrrev_i32_e32 v3, 31, v2
	v_lshl_add_u64 v[2:3], v[2:3], 2, s[30:31]
	v_ashrrev_i32_e32 v71, 31, v70
	v_ashrrev_i32_e32 v75, 31, v74
	v_ashrrev_i32_e32 v77, 31, v76
	v_ashrrev_i32_e32 v79, 31, v78
	v_ashrrev_i32_e32 v81, 31, v80
	v_ashrrev_i32_e32 v83, 31, v82
	v_ashrrev_i32_e32 v85, 31, v84
	global_load_dword v118, v[2:3], off
	v_lshl_add_u64 v[2:3], v[70:71], 2, s[30:31]
	v_lshl_add_u64 v[70:71], v[74:75], 2, s[30:31]
	v_lshl_add_u64 v[72:73], v[76:77], 2, s[30:31]
	v_lshl_add_u64 v[74:75], v[78:79], 2, s[30:31]
	v_lshl_add_u64 v[76:77], v[80:81], 2, s[30:31]
	v_lshl_add_u64 v[78:79], v[82:83], 2, s[30:31]
	v_lshl_add_u64 v[80:81], v[84:85], 2, s[30:31]
	global_load_dword v120, v[2:3], off
	s_nop 0
	global_load_dword v122, v[70:71], off
	s_nop 0
	global_load_dword v124, v[72:73], off
	s_nop 0
	global_load_dword v126, v[74:75], off
	s_nop 0
	global_load_dword v128, v[76:77], off
	s_nop 0
	global_load_dword v130, v[78:79], off
	global_load_dword v132, v[80:81], off
